# speedup vs baseline: 1.0052x; 1.0014x over previous
.LBB0_1027:
	v_lshl_or_b32 v158, s44, 8, v164
	v_ashrrev_i32_e32 v159, 31, v158
	v_lshl_add_u64 v[156:157], v[158:159], 2, s[6:7]
	global_load_dwordx4 v[140:143], v[156:157], off offset:16
	global_load_dwordx4 v[144:147], v[156:157], off
	v_lshl_add_u32 v160, s41, 8, v162
	v_ashrrev_i32_e32 v161, 31, v160
	s_mov_b64 s[20:21], 0x40000
	s_andn2_b64 vcc, exec, s[4:5]
	s_mov_b32 s42, 0xc000
	s_waitcnt vmcnt(0)
	v_pk_add_f32 v[148:149], v[142:143], 1.0 op_sel_hi:[1,0]
	v_pk_add_f32 v[150:151], v[140:141], 1.0 op_sel_hi:[1,0]
	global_load_dwordx4 v[166:169], v[156:157], off offset:528
	global_load_dwordx4 v[140:143], v[156:157], off offset:512
	v_lshlrev_b64 v[156:157], 11, v[160:161]
	v_lshl_add_u64 v[156:157], v[156:157], 0, v[158:159]
	v_lshlrev_b64 v[170:171], 1, v[156:157]
	v_pk_add_f32 v[154:155], v[144:145], 1.0 op_sel_hi:[1,0]
	v_pk_add_f32 v[152:153], v[146:147], 1.0 op_sel_hi:[1,0]
	s_waitcnt vmcnt(0)
	v_pk_add_f32 v[144:145], v[142:143], 1.0 op_sel_hi:[1,0]
	v_pk_add_f32 v[142:143], v[166:167], 1.0 op_sel_hi:[1,0]
	v_lshl_add_u64 v[166:167], s[50:51], 0, v[170:171]
	v_pk_add_f32 v[146:147], v[140:141], 1.0 op_sel_hi:[1,0]
	v_pk_add_f32 v[140:141], v[168:169], 1.0 op_sel_hi:[1,0]
	v_lshlrev_b32_e32 v184, 1, v156
	s_add_u32 s100, s50, 0x0
	s_addc_u32 s101, s51, 0
	global_load_dwordx4 v[176:179], v184, s[100:101]
	global_load_dwordx4 v[180:183], v184, s[100:101] offset:256
	s_add_u32 s100, s100, 0x10000
	s_addc_u32 s101, s101, 0
	global_load_dwordx4 v[188:191], v184, s[100:101]
	global_load_dwordx4 v[192:195], v184, s[100:101] offset:256
	s_add_u32 s100, s100, 0x10000
	s_addc_u32 s101, s101, 0
	global_load_dwordx4 v[196:199], v184, s[100:101]
	global_load_dwordx4 v[200:203], v184, s[100:101] offset:256
	s_add_u32 s100, s100, 0x10000
	s_addc_u32 s101, s101, 0
	global_load_dwordx4 v[204:207], v184, s[100:101]
	global_load_dwordx4 v[218:221], v184, s[100:101] offset:256
	s_waitcnt vmcnt(0)
	v_or_b32_e32 v170, 0x100, v170
	v_lshlrev_b32_e32 v172, 16, v176
	v_and_b32_e32 v173, 0xffff0000, v176
	v_lshlrev_b32_e32 v166, 16, v177
	v_and_b32_e32 v167, 0xffff0000, v177
	v_lshlrev_b32_e32 v174, 16, v178
	v_and_b32_e32 v175, 0xffff0000, v178
	v_pk_mul_f32 v[166:167], v[166:167], s[60:61] op_sel_hi:[1,0]
	v_lshlrev_b32_e32 v168, 16, v179
	v_and_b32_e32 v169, 0xffff0000, v179
	v_pk_mul_f32 v[172:173], v[172:173], s[60:61] op_sel_hi:[1,0]
	v_pk_fma_f32 v[128:129], v[128:129], v[152:153], v[166:167]
	v_pk_mul_f32 v[166:167], v[174:175], s[60:61] op_sel_hi:[1,0]
	v_pk_fma_f32 v[126:127], v[126:127], v[154:155], v[172:173]
	v_pk_mul_f32 v[168:169], v[168:169], s[60:61] op_sel_hi:[1,0]
	v_pk_fma_f32 v[122:123], v[122:123], v[150:151], v[166:167]
	v_lshl_add_u64 v[166:167], v[156:157], 2, s[36:37]
	v_pk_fma_f32 v[124:125], v[124:125], v[148:149], v[168:169]
	global_store_dwordx4 v[166:167], v[126:129], off
	global_store_dwordx4 v[166:167], v[122:125], off offset:16
	s_nop 1
	v_lshl_add_u64 v[122:123], s[50:51], 0, v[170:171]
	v_lshlrev_b32_e32 v126, 16, v180
	v_and_b32_e32 v127, 0xffff0000, v180
	v_lshlrev_b32_e32 v122, 16, v181
	v_and_b32_e32 v123, 0xffff0000, v181
	v_lshlrev_b32_e32 v128, 16, v182
	v_and_b32_e32 v129, 0xffff0000, v182
	v_pk_mul_f32 v[122:123], v[122:123], s[60:61] op_sel_hi:[1,0]
	v_lshlrev_b32_e32 v124, 16, v183
	v_and_b32_e32 v125, 0xffff0000, v183
	v_pk_mul_f32 v[126:127], v[126:127], s[60:61] op_sel_hi:[1,0]
	v_pk_fma_f32 v[120:121], v[120:121], v[144:145], v[122:123]
	v_pk_mul_f32 v[122:123], v[128:129], s[60:61] op_sel_hi:[1,0]
	v_pk_fma_f32 v[118:119], v[118:119], v[146:147], v[126:127]
	v_pk_mul_f32 v[124:125], v[124:125], s[60:61] op_sel_hi:[1,0]
	v_pk_fma_f32 v[114:115], v[114:115], v[142:143], v[122:123]
	v_pk_fma_f32 v[116:117], v[116:117], v[140:141], v[124:125]
	global_store_dwordx4 v[166:167], v[118:121], off offset:512
	global_store_dwordx4 v[166:167], v[114:117], off offset:528
	s_nop 1
	v_or_b32_e32 v114, 16, v160
	v_ashrrev_i32_e32 v115, 31, v114
	v_lshlrev_b64 v[114:115], 11, v[114:115]
	v_lshl_add_u64 v[118:119], v[114:115], 0, v[158:159]
	v_lshlrev_b64 v[120:121], 1, v[118:119]
	v_lshl_add_u64 v[114:115], s[50:51], 0, v[120:121]
	v_or_b32_e32 v120, 0x100, v120
	v_lshlrev_b32_e32 v122, 16, v188
	v_and_b32_e32 v123, 0xffff0000, v188
	v_lshlrev_b32_e32 v114, 16, v189
	v_and_b32_e32 v115, 0xffff0000, v189
	v_lshlrev_b32_e32 v124, 16, v190
	v_and_b32_e32 v125, 0xffff0000, v190
	v_pk_mul_f32 v[114:115], v[114:115], s[60:61] op_sel_hi:[1,0]
	v_lshlrev_b32_e32 v116, 16, v191
	v_and_b32_e32 v117, 0xffff0000, v191
	v_pk_mul_f32 v[122:123], v[122:123], s[60:61] op_sel_hi:[1,0]
	v_pk_fma_f32 v[112:113], v[112:113], v[152:153], v[114:115]
	v_pk_mul_f32 v[114:115], v[124:125], s[60:61] op_sel_hi:[1,0]
	v_pk_fma_f32 v[110:111], v[110:111], v[154:155], v[122:123]
	v_pk_mul_f32 v[116:117], v[116:117], s[60:61] op_sel_hi:[1,0]
	v_pk_fma_f32 v[106:107], v[106:107], v[150:151], v[114:115]
	v_lshl_add_u64 v[114:115], v[118:119], 2, s[36:37]
	v_pk_fma_f32 v[108:109], v[108:109], v[148:149], v[116:117]
	global_store_dwordx4 v[114:115], v[110:113], off
	global_store_dwordx4 v[114:115], v[106:109], off offset:16
	s_nop 1
	v_lshl_add_u64 v[106:107], s[50:51], 0, v[120:121]
	v_lshlrev_b32_e32 v110, 16, v192
	v_and_b32_e32 v111, 0xffff0000, v192
	v_lshlrev_b32_e32 v106, 16, v193
	v_and_b32_e32 v107, 0xffff0000, v193
	v_lshlrev_b32_e32 v112, 16, v194
	v_and_b32_e32 v113, 0xffff0000, v194
	v_pk_mul_f32 v[106:107], v[106:107], s[60:61] op_sel_hi:[1,0]
	v_lshlrev_b32_e32 v108, 16, v195
	v_and_b32_e32 v109, 0xffff0000, v195
	v_pk_mul_f32 v[110:111], v[110:111], s[60:61] op_sel_hi:[1,0]
	v_pk_fma_f32 v[104:105], v[104:105], v[144:145], v[106:107]
	v_pk_mul_f32 v[106:107], v[112:113], s[60:61] op_sel_hi:[1,0]
	v_pk_fma_f32 v[102:103], v[102:103], v[146:147], v[110:111]
	v_pk_mul_f32 v[108:109], v[108:109], s[60:61] op_sel_hi:[1,0]
	v_pk_fma_f32 v[98:99], v[98:99], v[142:143], v[106:107]
	v_pk_fma_f32 v[100:101], v[100:101], v[140:141], v[108:109]
	global_store_dwordx4 v[114:115], v[102:105], off offset:512
	global_store_dwordx4 v[114:115], v[98:101], off offset:528
	s_nop 1
	v_or_b32_e32 v98, 32, v160
	v_ashrrev_i32_e32 v99, 31, v98
	v_lshlrev_b64 v[98:99], 11, v[98:99]
	v_lshl_add_u64 v[102:103], v[98:99], 0, v[158:159]
	v_lshlrev_b64 v[104:105], 1, v[102:103]
	v_lshl_add_u64 v[98:99], s[50:51], 0, v[104:105]
	v_or_b32_e32 v104, 0x100, v104
	v_lshlrev_b32_e32 v106, 16, v196
	v_and_b32_e32 v107, 0xffff0000, v196
	v_lshlrev_b32_e32 v98, 16, v197
	v_and_b32_e32 v99, 0xffff0000, v197
	v_lshlrev_b32_e32 v108, 16, v198
	v_and_b32_e32 v109, 0xffff0000, v198
	v_pk_mul_f32 v[98:99], v[98:99], s[60:61] op_sel_hi:[1,0]
	v_lshlrev_b32_e32 v100, 16, v199
	v_and_b32_e32 v101, 0xffff0000, v199
	v_pk_mul_f32 v[106:107], v[106:107], s[60:61] op_sel_hi:[1,0]
	v_pk_fma_f32 v[96:97], v[96:97], v[152:153], v[98:99]
	v_pk_mul_f32 v[98:99], v[108:109], s[60:61] op_sel_hi:[1,0]
	v_pk_fma_f32 v[94:95], v[94:95], v[154:155], v[106:107]
	v_pk_mul_f32 v[100:101], v[100:101], s[60:61] op_sel_hi:[1,0]
	v_pk_fma_f32 v[90:91], v[90:91], v[150:151], v[98:99]
	v_lshl_add_u64 v[98:99], v[102:103], 2, s[36:37]
	v_pk_fma_f32 v[92:93], v[92:93], v[148:149], v[100:101]
	global_store_dwordx4 v[98:99], v[94:97], off
	global_store_dwordx4 v[98:99], v[90:93], off offset:16
	s_nop 1
	v_lshl_add_u64 v[90:91], s[50:51], 0, v[104:105]
	v_lshlrev_b32_e32 v94, 16, v200
	v_and_b32_e32 v95, 0xffff0000, v200
	v_lshlrev_b32_e32 v90, 16, v201
	v_and_b32_e32 v91, 0xffff0000, v201
	v_lshlrev_b32_e32 v96, 16, v202
	v_and_b32_e32 v97, 0xffff0000, v202
	v_pk_mul_f32 v[90:91], v[90:91], s[60:61] op_sel_hi:[1,0]
	v_lshlrev_b32_e32 v92, 16, v203
	v_and_b32_e32 v93, 0xffff0000, v203
	v_pk_mul_f32 v[94:95], v[94:95], s[60:61] op_sel_hi:[1,0]
	v_pk_fma_f32 v[88:89], v[88:89], v[144:145], v[90:91]
	v_pk_mul_f32 v[90:91], v[96:97], s[60:61] op_sel_hi:[1,0]
	v_pk_fma_f32 v[86:87], v[86:87], v[146:147], v[94:95]
	v_pk_mul_f32 v[92:93], v[92:93], s[60:61] op_sel_hi:[1,0]
	v_pk_fma_f32 v[82:83], v[82:83], v[142:143], v[90:91]
	v_pk_fma_f32 v[84:85], v[84:85], v[140:141], v[92:93]
	global_store_dwordx4 v[98:99], v[86:89], off offset:512
	global_store_dwordx4 v[98:99], v[82:85], off offset:528
	s_nop 1
	v_or_b32_e32 v82, 48, v160
	v_ashrrev_i32_e32 v83, 31, v82
	v_lshlrev_b64 v[82:83], 11, v[82:83]
	v_lshl_add_u64 v[86:87], v[82:83], 0, v[158:159]
	v_lshlrev_b64 v[88:89], 1, v[86:87]
	v_lshl_add_u64 v[82:83], s[50:51], 0, v[88:89]
	v_or_b32_e32 v88, 0x100, v88
	v_lshlrev_b32_e32 v90, 16, v204
	v_and_b32_e32 v91, 0xffff0000, v204
	v_lshlrev_b32_e32 v82, 16, v205
	v_and_b32_e32 v83, 0xffff0000, v205
	v_lshlrev_b32_e32 v92, 16, v206
	v_and_b32_e32 v93, 0xffff0000, v206
	v_pk_mul_f32 v[82:83], v[82:83], s[60:61] op_sel_hi:[1,0]
	v_lshlrev_b32_e32 v84, 16, v207
	v_and_b32_e32 v85, 0xffff0000, v207
	v_pk_mul_f32 v[90:91], v[90:91], s[60:61] op_sel_hi:[1,0]
	v_pk_fma_f32 v[80:81], v[80:81], v[152:153], v[82:83]
	v_pk_mul_f32 v[82:83], v[92:93], s[60:61] op_sel_hi:[1,0]
	v_pk_fma_f32 v[78:79], v[78:79], v[154:155], v[90:91]
	v_pk_mul_f32 v[84:85], v[84:85], s[60:61] op_sel_hi:[1,0]
	v_pk_fma_f32 v[74:75], v[74:75], v[150:151], v[82:83]
	v_lshl_add_u64 v[82:83], v[86:87], 2, s[36:37]
	v_pk_fma_f32 v[76:77], v[76:77], v[148:149], v[84:85]
	global_store_dwordx4 v[82:83], v[78:81], off
	global_store_dwordx4 v[82:83], v[74:77], off offset:16
	s_nop 1
	v_lshl_add_u64 v[74:75], s[50:51], 0, v[88:89]
	v_lshlrev_b32_e32 v78, 16, v218
	v_and_b32_e32 v79, 0xffff0000, v218
	v_lshlrev_b32_e32 v74, 16, v219
	v_and_b32_e32 v75, 0xffff0000, v219
	v_lshlrev_b32_e32 v80, 16, v220
	v_and_b32_e32 v81, 0xffff0000, v220
	v_lshlrev_b32_e32 v76, 16, v221
	v_and_b32_e32 v77, 0xffff0000, v221
	v_pk_mul_f32 v[78:79], v[78:79], s[60:61] op_sel_hi:[1,0]
	v_pk_mul_f32 v[74:75], v[74:75], s[60:61] op_sel_hi:[1,0]
	v_pk_fma_f32 v[70:71], v[70:71], v[146:147], v[78:79]
	v_pk_fma_f32 v[72:73], v[72:73], v[144:145], v[74:75]
	v_pk_mul_f32 v[74:75], v[80:81], s[60:61] op_sel_hi:[1,0]
	v_pk_mul_f32 v[76:77], v[76:77], s[60:61] op_sel_hi:[1,0]
	v_pk_fma_f32 v[66:67], v[66:67], v[142:143], v[74:75]
	v_pk_fma_f32 v[68:69], v[68:69], v[140:141], v[76:77]
	global_store_dwordx4 v[82:83], v[70:73], off offset:512
	global_store_dwordx4 v[82:83], v[66:69], off offset:528
	s_nop 0
	v_lshl_add_u64 v[70:71], v[156:157], 0, s[20:21]
	v_lshlrev_b64 v[72:73], 1, v[70:71]
	v_lshl_add_u64 v[66:67], s[50:51], 0, v[72:73]
	v_lshlrev_b32_e32 v184, 1, v156
	s_add_u32 s100, s50, 0x80000
	s_addc_u32 s101, s51, 0
	global_load_dwordx4 v[176:179], v184, s[100:101]
	global_load_dwordx4 v[180:183], v184, s[100:101] offset:256
	s_add_u32 s100, s100, 0x10000
	s_addc_u32 s101, s101, 0
	global_load_dwordx4 v[188:191], v184, s[100:101]
	global_load_dwordx4 v[192:195], v184, s[100:101] offset:256
	s_add_u32 s100, s100, 0x10000
	s_addc_u32 s101, s101, 0
	global_load_dwordx4 v[196:199], v184, s[100:101]
	global_load_dwordx4 v[200:203], v184, s[100:101] offset:256
	s_add_u32 s100, s100, 0x10000
	s_addc_u32 s101, s101, 0
	global_load_dwordx4 v[204:207], v184, s[100:101]
	global_load_dwordx4 v[218:221], v184, s[100:101] offset:256
	s_waitcnt vmcnt(0)
	v_or_b32_e32 v72, 0x100, v72
	s_mov_b64 s[20:21], 0x48000
	v_lshlrev_b32_e32 v74, 16, v176
	v_and_b32_e32 v75, 0xffff0000, v176
	v_lshlrev_b32_e32 v66, 16, v177
	v_and_b32_e32 v67, 0xffff0000, v177
	v_lshlrev_b32_e32 v76, 16, v178
	v_and_b32_e32 v77, 0xffff0000, v178
	v_pk_mul_f32 v[66:67], v[66:67], s[60:61] op_sel_hi:[1,0]
	v_lshlrev_b32_e32 v68, 16, v179
	v_and_b32_e32 v69, 0xffff0000, v179
	v_pk_mul_f32 v[74:75], v[74:75], s[60:61] op_sel_hi:[1,0]
	v_pk_fma_f32 v[64:65], v[64:65], v[152:153], v[66:67]
	v_pk_mul_f32 v[66:67], v[76:77], s[60:61] op_sel_hi:[1,0]
	v_pk_fma_f32 v[62:63], v[62:63], v[154:155], v[74:75]
	v_pk_mul_f32 v[68:69], v[68:69], s[60:61] op_sel_hi:[1,0]
	v_pk_fma_f32 v[58:59], v[58:59], v[150:151], v[66:67]
	v_lshl_add_u64 v[66:67], v[70:71], 2, s[36:37]
	v_pk_fma_f32 v[60:61], v[60:61], v[148:149], v[68:69]
	global_store_dwordx4 v[66:67], v[62:65], off
	global_store_dwordx4 v[66:67], v[58:61], off offset:16
	s_nop 1
	v_lshl_add_u64 v[58:59], s[50:51], 0, v[72:73]
	v_lshlrev_b32_e32 v62, 16, v180
	v_and_b32_e32 v63, 0xffff0000, v180
	v_lshlrev_b32_e32 v58, 16, v181
	v_and_b32_e32 v59, 0xffff0000, v181
	v_lshlrev_b32_e32 v64, 16, v182
	v_and_b32_e32 v65, 0xffff0000, v182
	v_lshlrev_b32_e32 v60, 16, v183
	v_and_b32_e32 v61, 0xffff0000, v183
	v_pk_mul_f32 v[62:63], v[62:63], s[60:61] op_sel_hi:[1,0]
	v_pk_mul_f32 v[58:59], v[58:59], s[60:61] op_sel_hi:[1,0]
	v_pk_fma_f32 v[54:55], v[54:55], v[146:147], v[62:63]
	v_pk_fma_f32 v[56:57], v[56:57], v[144:145], v[58:59]
	v_pk_mul_f32 v[58:59], v[64:65], s[60:61] op_sel_hi:[1,0]
	v_pk_mul_f32 v[60:61], v[60:61], s[60:61] op_sel_hi:[1,0]
	v_pk_fma_f32 v[50:51], v[50:51], v[142:143], v[58:59]
	v_pk_fma_f32 v[52:53], v[52:53], v[140:141], v[60:61]
	global_store_dwordx4 v[66:67], v[54:57], off offset:512
	global_store_dwordx4 v[66:67], v[50:53], off offset:528
	s_nop 0
	v_lshl_add_u64 v[54:55], v[156:157], 0, s[20:21]
	v_lshlrev_b64 v[56:57], 1, v[54:55]
	v_lshl_add_u64 v[50:51], s[50:51], 0, v[56:57]
	v_or_b32_e32 v56, 0x100, v56
	s_mov_b64 s[20:21], 0x50000
	v_lshlrev_b32_e32 v58, 16, v188
	v_and_b32_e32 v59, 0xffff0000, v188
	v_lshlrev_b32_e32 v50, 16, v189
	v_and_b32_e32 v51, 0xffff0000, v189
	v_lshlrev_b32_e32 v60, 16, v190
	v_and_b32_e32 v61, 0xffff0000, v190
	v_pk_mul_f32 v[50:51], v[50:51], s[60:61] op_sel_hi:[1,0]
	v_lshlrev_b32_e32 v52, 16, v191
	v_and_b32_e32 v53, 0xffff0000, v191
	v_pk_mul_f32 v[58:59], v[58:59], s[60:61] op_sel_hi:[1,0]
	v_pk_fma_f32 v[48:49], v[48:49], v[152:153], v[50:51]
	v_pk_mul_f32 v[50:51], v[60:61], s[60:61] op_sel_hi:[1,0]
	v_pk_fma_f32 v[46:47], v[46:47], v[154:155], v[58:59]
	v_pk_mul_f32 v[52:53], v[52:53], s[60:61] op_sel_hi:[1,0]
	v_pk_fma_f32 v[42:43], v[42:43], v[150:151], v[50:51]
	v_lshl_add_u64 v[50:51], v[54:55], 2, s[36:37]
	v_pk_fma_f32 v[44:45], v[44:45], v[148:149], v[52:53]
	global_store_dwordx4 v[50:51], v[46:49], off
	global_store_dwordx4 v[50:51], v[42:45], off offset:16
	s_nop 1
	v_lshl_add_u64 v[42:43], s[50:51], 0, v[56:57]
	v_lshlrev_b32_e32 v46, 16, v192
	v_and_b32_e32 v47, 0xffff0000, v192
	v_lshlrev_b32_e32 v42, 16, v193
	v_and_b32_e32 v43, 0xffff0000, v193
	v_lshlrev_b32_e32 v48, 16, v194
	v_and_b32_e32 v49, 0xffff0000, v194
	v_lshlrev_b32_e32 v44, 16, v195
	v_and_b32_e32 v45, 0xffff0000, v195
	v_pk_mul_f32 v[46:47], v[46:47], s[60:61] op_sel_hi:[1,0]
	v_pk_mul_f32 v[42:43], v[42:43], s[60:61] op_sel_hi:[1,0]
	v_pk_fma_f32 v[38:39], v[38:39], v[146:147], v[46:47]
	v_pk_fma_f32 v[40:41], v[40:41], v[144:145], v[42:43]
	v_pk_mul_f32 v[42:43], v[48:49], s[60:61] op_sel_hi:[1,0]
	v_pk_mul_f32 v[44:45], v[44:45], s[60:61] op_sel_hi:[1,0]
	v_pk_fma_f32 v[34:35], v[34:35], v[142:143], v[42:43]
	v_pk_fma_f32 v[36:37], v[36:37], v[140:141], v[44:45]
	global_store_dwordx4 v[50:51], v[38:41], off offset:512
	global_store_dwordx4 v[50:51], v[34:37], off offset:528
	s_nop 0
	v_lshl_add_u64 v[38:39], v[156:157], 0, s[20:21]
	v_lshlrev_b64 v[40:41], 1, v[38:39]
	v_lshl_add_u64 v[34:35], s[50:51], 0, v[40:41]
	v_or_b32_e32 v40, 0x100, v40
	s_mov_b64 s[20:21], 0x58000
	v_lshlrev_b32_e32 v42, 16, v196
	v_and_b32_e32 v43, 0xffff0000, v196
	v_lshlrev_b32_e32 v34, 16, v197
	v_and_b32_e32 v35, 0xffff0000, v197
	v_lshlrev_b32_e32 v44, 16, v198
	v_and_b32_e32 v45, 0xffff0000, v198
	v_pk_mul_f32 v[34:35], v[34:35], s[60:61] op_sel_hi:[1,0]
	v_lshlrev_b32_e32 v36, 16, v199
	v_and_b32_e32 v37, 0xffff0000, v199
	v_pk_mul_f32 v[42:43], v[42:43], s[60:61] op_sel_hi:[1,0]
	v_pk_fma_f32 v[32:33], v[32:33], v[152:153], v[34:35]
	v_pk_mul_f32 v[34:35], v[44:45], s[60:61] op_sel_hi:[1,0]
	v_pk_fma_f32 v[30:31], v[30:31], v[154:155], v[42:43]
	v_pk_mul_f32 v[36:37], v[36:37], s[60:61] op_sel_hi:[1,0]
	v_pk_fma_f32 v[26:27], v[26:27], v[150:151], v[34:35]
	v_lshl_add_u64 v[34:35], v[38:39], 2, s[36:37]
	v_pk_fma_f32 v[28:29], v[28:29], v[148:149], v[36:37]
	global_store_dwordx4 v[34:35], v[30:33], off
	global_store_dwordx4 v[34:35], v[26:29], off offset:16
	s_nop 1
	v_lshl_add_u64 v[26:27], s[50:51], 0, v[40:41]
	v_lshlrev_b32_e32 v30, 16, v200
	v_and_b32_e32 v31, 0xffff0000, v200
	v_lshlrev_b32_e32 v26, 16, v201
	v_and_b32_e32 v27, 0xffff0000, v201
	v_lshlrev_b32_e32 v32, 16, v202
	v_and_b32_e32 v33, 0xffff0000, v202
	v_lshlrev_b32_e32 v28, 16, v203
	v_and_b32_e32 v29, 0xffff0000, v203
	v_pk_mul_f32 v[30:31], v[30:31], s[60:61] op_sel_hi:[1,0]
	v_pk_mul_f32 v[26:27], v[26:27], s[60:61] op_sel_hi:[1,0]
	v_pk_fma_f32 v[22:23], v[22:23], v[146:147], v[30:31]
	v_pk_fma_f32 v[24:25], v[24:25], v[144:145], v[26:27]
	v_pk_mul_f32 v[26:27], v[32:33], s[60:61] op_sel_hi:[1,0]
	v_pk_mul_f32 v[28:29], v[28:29], s[60:61] op_sel_hi:[1,0]
	v_pk_fma_f32 v[18:19], v[18:19], v[142:143], v[26:27]
	v_pk_fma_f32 v[20:21], v[20:21], v[140:141], v[28:29]
	global_store_dwordx4 v[34:35], v[22:25], off offset:512
	global_store_dwordx4 v[34:35], v[18:21], off offset:528
	s_nop 0
	v_lshl_add_u64 v[22:23], v[156:157], 0, s[20:21]
	v_lshlrev_b64 v[24:25], 1, v[22:23]
	v_lshl_add_u64 v[18:19], s[50:51], 0, v[24:25]
	v_or_b32_e32 v24, 0x100, v24
	s_mov_b64 s[20:21], -1
	v_lshlrev_b32_e32 v26, 16, v204
	v_and_b32_e32 v27, 0xffff0000, v204
	v_lshlrev_b32_e32 v18, 16, v205
	v_and_b32_e32 v19, 0xffff0000, v205
	v_lshlrev_b32_e32 v28, 16, v206
	v_and_b32_e32 v29, 0xffff0000, v206
	v_pk_mul_f32 v[18:19], v[18:19], s[60:61] op_sel_hi:[1,0]
	v_lshlrev_b32_e32 v20, 16, v207
	v_and_b32_e32 v21, 0xffff0000, v207
	v_pk_mul_f32 v[26:27], v[26:27], s[60:61] op_sel_hi:[1,0]
	v_pk_fma_f32 v[16:17], v[16:17], v[152:153], v[18:19]
	v_pk_mul_f32 v[18:19], v[28:29], s[60:61] op_sel_hi:[1,0]
	v_pk_fma_f32 v[14:15], v[14:15], v[154:155], v[26:27]
	v_pk_mul_f32 v[20:21], v[20:21], s[60:61] op_sel_hi:[1,0]
	v_pk_fma_f32 v[10:11], v[10:11], v[150:151], v[18:19]
	v_lshl_add_u64 v[18:19], v[22:23], 2, s[36:37]
	v_pk_fma_f32 v[12:13], v[12:13], v[148:149], v[20:21]
	global_store_dwordx4 v[18:19], v[14:17], off
	global_store_dwordx4 v[18:19], v[10:13], off offset:16
	s_nop 1
	v_lshl_add_u64 v[10:11], s[50:51], 0, v[24:25]
	v_lshlrev_b32_e32 v14, 16, v218
	v_and_b32_e32 v15, 0xffff0000, v218
	v_lshlrev_b32_e32 v10, 16, v219
	v_and_b32_e32 v11, 0xffff0000, v219
	v_lshlrev_b32_e32 v16, 16, v220
	v_and_b32_e32 v17, 0xffff0000, v220
	v_lshlrev_b32_e32 v12, 16, v221
	v_and_b32_e32 v13, 0xffff0000, v221
	v_pk_mul_f32 v[14:15], v[14:15], s[60:61] op_sel_hi:[1,0]
	v_pk_mul_f32 v[10:11], v[10:11], s[60:61] op_sel_hi:[1,0]
	v_pk_fma_f32 v[6:7], v[6:7], v[146:147], v[14:15]
	v_pk_fma_f32 v[8:9], v[8:9], v[144:145], v[10:11]
	v_pk_mul_f32 v[10:11], v[16:17], s[60:61] op_sel_hi:[1,0]
	v_pk_mul_f32 v[12:13], v[12:13], s[60:61] op_sel_hi:[1,0]
	v_pk_fma_f32 v[2:3], v[2:3], v[142:143], v[10:11]
	v_pk_fma_f32 v[4:5], v[4:5], v[140:141], v[12:13]
	global_store_dwordx4 v[18:19], v[6:9], off offset:512
	global_store_dwordx4 v[18:19], v[2:5], off offset:528
	s_cbranch_vccnz .LBB0_1016
	s_andn2_b64 vcc, exec, s[8:9]
	s_cbranch_vccnz .LBB0_1015
	s_barrier
	s_branch .LBB0_1015

.LBB0_1049:
	v_lshl_or_b32 v160, s40, 8, v164
	v_ashrrev_i32_e32 v161, 31, v160
	v_lshl_add_u64 v[166:167], v[160:161], 2, s[6:7]
	global_load_dwordx4 v[140:143], v[166:167], off offset:16
	global_load_dwordx4 v[144:147], v[166:167], off
	v_lshlrev_b64 v[160:161], 1, v[160:161]
	s_mov_b32 s3, 0x80000
	s_mov_b64 s[18:19], 0x80000
	s_mov_b32 s42, 0xc000
	s_waitcnt vmcnt(0)
	v_pk_add_f32 v[148:149], v[142:143], 1.0 op_sel_hi:[1,0]
	v_pk_add_f32 v[150:151], v[140:141], 1.0 op_sel_hi:[1,0]
	global_load_dwordx4 v[156:159], v[166:167], off offset:528
	global_load_dwordx4 v[140:143], v[166:167], off offset:512
	v_pk_add_f32 v[152:153], v[146:147], 1.0 op_sel_hi:[1,0]
	v_pk_add_f32 v[154:155], v[144:145], 1.0 op_sel_hi:[1,0]
	s_waitcnt vmcnt(0)
	v_pk_add_f32 v[146:147], v[140:141], 1.0 op_sel_hi:[1,0]
	v_pk_add_f32 v[140:141], v[158:159], 1.0 op_sel_hi:[1,0]
	v_lshl_add_u32 v158, s35, 8, v162
	v_ashrrev_i32_e32 v159, 31, v158
	v_pk_add_f32 v[144:145], v[142:143], 1.0 op_sel_hi:[1,0]
	v_pk_add_f32 v[142:143], v[156:157], 1.0 op_sel_hi:[1,0]
	v_lshlrev_b64 v[156:157], 12, v[158:159]
	v_lshl_add_u64 v[156:157], s[50:51], 0, v[156:157]
	v_lshl_add_u64 v[156:157], v[156:157], 0, v[160:161]
	v_lshl_add_u32 v184, v158, 12, v160
	s_add_u32 s100, s50, 0x0
	s_addc_u32 s101, s51, 0
	global_load_dwordx4 v[176:179], v184, s[100:101]
	global_load_dwordx4 v[180:183], v184, s[100:101] offset:256
	s_add_u32 s100, s100, 0x10000
	s_addc_u32 s101, s101, 0
	global_load_dwordx4 v[188:191], v184, s[100:101]
	global_load_dwordx4 v[192:195], v184, s[100:101] offset:256
	s_add_u32 s100, s100, 0x10000
	s_addc_u32 s101, s101, 0
	global_load_dwordx4 v[196:199], v184, s[100:101]
	global_load_dwordx4 v[200:203], v184, s[100:101] offset:256
	s_add_u32 s100, s100, 0x10000
	s_addc_u32 s101, s101, 0
	global_load_dwordx4 v[204:207], v184, s[100:101]
	global_load_dwordx4 v[218:221], v184, s[100:101] offset:256
	s_waitcnt vmcnt(0)
	v_lshlrev_b32_e32 v170, 16, v176
	v_and_b32_e32 v171, 0xffff0000, v176
	v_lshlrev_b32_e32 v166, 16, v177
	v_and_b32_e32 v167, 0xffff0000, v177
	v_lshlrev_b32_e32 v172, 16, v178
	v_and_b32_e32 v173, 0xffff0000, v178
	v_lshlrev_b32_e32 v168, 16, v179
	v_and_b32_e32 v169, 0xffff0000, v179
	v_pk_mul_f32 v[166:167], v[166:167], s[60:61] op_sel_hi:[1,0]
	v_pk_mul_f32 v[170:171], v[170:171], s[60:61] op_sel_hi:[1,0]
	v_pk_fma_f32 v[128:129], v[128:129], v[152:153], v[166:167]
	v_pk_mul_f32 v[166:167], v[172:173], s[60:61] op_sel_hi:[1,0]
	v_pk_mul_f32 v[168:169], v[168:169], s[60:61] op_sel_hi:[1,0]
	v_pk_fma_f32 v[126:127], v[126:127], v[154:155], v[170:171]
	v_pk_fma_f32 v[168:169], v[124:125], v[148:149], v[168:169]
	v_pk_fma_f32 v[124:125], v[122:123], v[150:151], v[166:167]
	v_cvt_pk_bf16_f32 v122, v126, v127
	v_cvt_pk_bf16_f32 v123, v128, v129
	v_cvt_pk_bf16_f32 v124, v124, v125
	v_cvt_pk_bf16_f32 v125, v168, v169
	global_store_dwordx4 v[156:157], v[122:125], off
	v_lshlrev_b32_e32 v126, 16, v180
	v_and_b32_e32 v127, 0xffff0000, v180
	v_lshlrev_b32_e32 v122, 16, v181
	v_and_b32_e32 v123, 0xffff0000, v181
	v_lshlrev_b32_e32 v128, 16, v182
	v_and_b32_e32 v129, 0xffff0000, v182
	v_lshlrev_b32_e32 v124, 16, v183
	v_and_b32_e32 v125, 0xffff0000, v183
	v_pk_mul_f32 v[122:123], v[122:123], s[60:61] op_sel_hi:[1,0]
	v_pk_mul_f32 v[126:127], v[126:127], s[60:61] op_sel_hi:[1,0]
	v_pk_fma_f32 v[120:121], v[120:121], v[144:145], v[122:123]
	v_pk_mul_f32 v[122:123], v[128:129], s[60:61] op_sel_hi:[1,0]
	v_pk_mul_f32 v[124:125], v[124:125], s[60:61] op_sel_hi:[1,0]
	v_pk_fma_f32 v[118:119], v[118:119], v[146:147], v[126:127]
	v_pk_fma_f32 v[124:125], v[116:117], v[140:141], v[124:125]
	v_pk_fma_f32 v[116:117], v[114:115], v[142:143], v[122:123]
	v_cvt_pk_bf16_f32 v114, v118, v119
	v_cvt_pk_bf16_f32 v115, v120, v121
	v_cvt_pk_bf16_f32 v116, v116, v117
	v_cvt_pk_bf16_f32 v117, v124, v125
	global_store_dwordx4 v[156:157], v[114:117], off offset:256
	s_nop 1
	v_or_b32_e32 v114, 16, v158
	v_ashrrev_i32_e32 v115, 31, v114
	v_lshlrev_b64 v[114:115], 12, v[114:115]
	v_lshl_add_u64 v[114:115], s[50:51], 0, v[114:115]
	v_lshl_add_u64 v[118:119], v[114:115], 0, v[160:161]
	v_lshlrev_b32_e32 v120, 16, v188
	v_and_b32_e32 v121, 0xffff0000, v188
	v_lshlrev_b32_e32 v114, 16, v189
	v_and_b32_e32 v115, 0xffff0000, v189
	v_lshlrev_b32_e32 v122, 16, v190
	v_and_b32_e32 v123, 0xffff0000, v190
	v_lshlrev_b32_e32 v116, 16, v191
	v_and_b32_e32 v117, 0xffff0000, v191
	v_pk_mul_f32 v[114:115], v[114:115], s[60:61] op_sel_hi:[1,0]
	v_pk_mul_f32 v[120:121], v[120:121], s[60:61] op_sel_hi:[1,0]
	v_pk_fma_f32 v[112:113], v[112:113], v[152:153], v[114:115]
	v_pk_mul_f32 v[114:115], v[122:123], s[60:61] op_sel_hi:[1,0]
	v_pk_mul_f32 v[116:117], v[116:117], s[60:61] op_sel_hi:[1,0]
	v_pk_fma_f32 v[110:111], v[110:111], v[154:155], v[120:121]
	v_pk_fma_f32 v[116:117], v[108:109], v[148:149], v[116:117]
	v_pk_fma_f32 v[108:109], v[106:107], v[150:151], v[114:115]
	v_cvt_pk_bf16_f32 v106, v110, v111
	v_cvt_pk_bf16_f32 v107, v112, v113
	v_cvt_pk_bf16_f32 v108, v108, v109
	v_cvt_pk_bf16_f32 v109, v116, v117
	global_store_dwordx4 v[118:119], v[106:109], off
	v_lshlrev_b32_e32 v110, 16, v192
	v_and_b32_e32 v111, 0xffff0000, v192
	v_lshlrev_b32_e32 v106, 16, v193
	v_and_b32_e32 v107, 0xffff0000, v193
	v_lshlrev_b32_e32 v112, 16, v194
	v_and_b32_e32 v113, 0xffff0000, v194
	v_lshlrev_b32_e32 v108, 16, v195
	v_and_b32_e32 v109, 0xffff0000, v195
	v_pk_mul_f32 v[106:107], v[106:107], s[60:61] op_sel_hi:[1,0]
	v_pk_mul_f32 v[110:111], v[110:111], s[60:61] op_sel_hi:[1,0]
	v_pk_fma_f32 v[104:105], v[104:105], v[144:145], v[106:107]
	v_pk_mul_f32 v[106:107], v[112:113], s[60:61] op_sel_hi:[1,0]
	v_pk_mul_f32 v[108:109], v[108:109], s[60:61] op_sel_hi:[1,0]
	v_pk_fma_f32 v[102:103], v[102:103], v[146:147], v[110:111]
	v_pk_fma_f32 v[108:109], v[100:101], v[140:141], v[108:109]
	v_pk_fma_f32 v[100:101], v[98:99], v[142:143], v[106:107]
	v_cvt_pk_bf16_f32 v98, v102, v103
	v_cvt_pk_bf16_f32 v99, v104, v105
	v_cvt_pk_bf16_f32 v100, v100, v101
	v_cvt_pk_bf16_f32 v101, v108, v109
	global_store_dwordx4 v[118:119], v[98:101], off offset:256
	s_nop 1
	v_or_b32_e32 v98, 32, v158
	v_ashrrev_i32_e32 v99, 31, v98
	v_lshlrev_b64 v[98:99], 12, v[98:99]
	v_lshl_add_u64 v[98:99], s[50:51], 0, v[98:99]
	v_lshl_add_u64 v[102:103], v[98:99], 0, v[160:161]
	v_lshlrev_b32_e32 v104, 16, v196
	v_and_b32_e32 v105, 0xffff0000, v196
	v_lshlrev_b32_e32 v98, 16, v197
	v_and_b32_e32 v99, 0xffff0000, v197
	v_lshlrev_b32_e32 v106, 16, v198
	v_and_b32_e32 v107, 0xffff0000, v198
	v_lshlrev_b32_e32 v100, 16, v199
	v_and_b32_e32 v101, 0xffff0000, v199
	v_pk_mul_f32 v[98:99], v[98:99], s[60:61] op_sel_hi:[1,0]
	v_pk_mul_f32 v[104:105], v[104:105], s[60:61] op_sel_hi:[1,0]
	v_pk_fma_f32 v[96:97], v[96:97], v[152:153], v[98:99]
	v_pk_mul_f32 v[98:99], v[106:107], s[60:61] op_sel_hi:[1,0]
	v_pk_mul_f32 v[100:101], v[100:101], s[60:61] op_sel_hi:[1,0]
	v_pk_fma_f32 v[94:95], v[94:95], v[154:155], v[104:105]
	v_pk_fma_f32 v[100:101], v[92:93], v[148:149], v[100:101]
	v_pk_fma_f32 v[92:93], v[90:91], v[150:151], v[98:99]
	v_cvt_pk_bf16_f32 v90, v94, v95
	v_cvt_pk_bf16_f32 v91, v96, v97
	v_cvt_pk_bf16_f32 v92, v92, v93
	v_cvt_pk_bf16_f32 v93, v100, v101
	global_store_dwordx4 v[102:103], v[90:93], off
	v_lshlrev_b32_e32 v94, 16, v200
	v_and_b32_e32 v95, 0xffff0000, v200
	v_lshlrev_b32_e32 v90, 16, v201
	v_and_b32_e32 v91, 0xffff0000, v201
	v_lshlrev_b32_e32 v96, 16, v202
	v_and_b32_e32 v97, 0xffff0000, v202
	v_lshlrev_b32_e32 v92, 16, v203
	v_and_b32_e32 v93, 0xffff0000, v203
	v_pk_mul_f32 v[90:91], v[90:91], s[60:61] op_sel_hi:[1,0]
	v_pk_mul_f32 v[94:95], v[94:95], s[60:61] op_sel_hi:[1,0]
	v_pk_fma_f32 v[88:89], v[88:89], v[144:145], v[90:91]
	v_pk_mul_f32 v[90:91], v[96:97], s[60:61] op_sel_hi:[1,0]
	v_pk_mul_f32 v[92:93], v[92:93], s[60:61] op_sel_hi:[1,0]
	v_pk_fma_f32 v[86:87], v[86:87], v[146:147], v[94:95]
	v_pk_fma_f32 v[92:93], v[84:85], v[140:141], v[92:93]
	v_pk_fma_f32 v[84:85], v[82:83], v[142:143], v[90:91]
	v_cvt_pk_bf16_f32 v82, v86, v87
	v_cvt_pk_bf16_f32 v83, v88, v89
	v_cvt_pk_bf16_f32 v84, v84, v85
	v_cvt_pk_bf16_f32 v85, v92, v93
	global_store_dwordx4 v[102:103], v[82:85], off offset:256
	s_nop 1
	v_or_b32_e32 v82, 48, v158
	v_ashrrev_i32_e32 v83, 31, v82
	v_lshlrev_b64 v[82:83], 12, v[82:83]
	v_lshl_add_u64 v[82:83], s[50:51], 0, v[82:83]
	v_lshl_add_u64 v[86:87], v[82:83], 0, v[160:161]
	v_lshlrev_b32_e32 v88, 16, v204
	v_and_b32_e32 v89, 0xffff0000, v204
	v_lshlrev_b32_e32 v82, 16, v205
	v_and_b32_e32 v83, 0xffff0000, v205
	v_lshlrev_b32_e32 v90, 16, v206
	v_and_b32_e32 v91, 0xffff0000, v206
	v_lshlrev_b32_e32 v84, 16, v207
	v_and_b32_e32 v85, 0xffff0000, v207
	v_pk_mul_f32 v[82:83], v[82:83], s[60:61] op_sel_hi:[1,0]
	v_pk_mul_f32 v[88:89], v[88:89], s[60:61] op_sel_hi:[1,0]
	v_pk_fma_f32 v[80:81], v[80:81], v[152:153], v[82:83]
	v_pk_mul_f32 v[82:83], v[90:91], s[60:61] op_sel_hi:[1,0]
	v_pk_mul_f32 v[84:85], v[84:85], s[60:61] op_sel_hi:[1,0]
	v_pk_fma_f32 v[78:79], v[78:79], v[154:155], v[88:89]
	v_pk_fma_f32 v[84:85], v[76:77], v[148:149], v[84:85]
	v_pk_fma_f32 v[76:77], v[74:75], v[150:151], v[82:83]
	v_cvt_pk_bf16_f32 v74, v78, v79
	v_cvt_pk_bf16_f32 v75, v80, v81
	v_cvt_pk_bf16_f32 v76, v76, v77
	v_cvt_pk_bf16_f32 v77, v84, v85
	global_store_dwordx4 v[86:87], v[74:77], off
	v_lshlrev_b32_e32 v78, 16, v218
	v_and_b32_e32 v79, 0xffff0000, v218
	v_lshlrev_b32_e32 v74, 16, v219
	v_and_b32_e32 v75, 0xffff0000, v219
	v_lshlrev_b32_e32 v80, 16, v220
	v_and_b32_e32 v81, 0xffff0000, v220
	v_lshlrev_b32_e32 v76, 16, v221
	v_and_b32_e32 v77, 0xffff0000, v221
	v_pk_mul_f32 v[74:75], v[74:75], s[60:61] op_sel_hi:[1,0]
	v_pk_mul_f32 v[78:79], v[78:79], s[60:61] op_sel_hi:[1,0]
	v_pk_fma_f32 v[72:73], v[72:73], v[144:145], v[74:75]
	v_pk_mul_f32 v[74:75], v[80:81], s[60:61] op_sel_hi:[1,0]
	v_pk_mul_f32 v[76:77], v[76:77], s[60:61] op_sel_hi:[1,0]
	v_pk_fma_f32 v[70:71], v[70:71], v[146:147], v[78:79]
	v_pk_fma_f32 v[76:77], v[68:69], v[140:141], v[76:77]
	v_pk_fma_f32 v[68:69], v[66:67], v[142:143], v[74:75]
	v_cvt_pk_bf16_f32 v67, v72, v73
	v_add_co_u32_e32 v72, vcc, s3, v156
	v_cvt_pk_bf16_f32 v66, v70, v71
	v_cvt_pk_bf16_f32 v68, v68, v69
	v_cvt_pk_bf16_f32 v69, v76, v77
	v_addc_co_u32_e32 v73, vcc, 0, v157, vcc
	global_store_dwordx4 v[86:87], v[66:69], off offset:256
	v_lshl_add_u32 v184, v158, 12, v160
	s_add_u32 s100, s50, 0x80000
	s_addc_u32 s101, s51, 0
	global_load_dwordx4 v[176:179], v184, s[100:101]
	global_load_dwordx4 v[180:183], v184, s[100:101] offset:256
	s_add_u32 s100, s100, 0x10000
	s_addc_u32 s101, s101, 0
	global_load_dwordx4 v[188:191], v184, s[100:101]
	global_load_dwordx4 v[192:195], v184, s[100:101] offset:256
	s_add_u32 s100, s100, 0x10000
	s_addc_u32 s101, s101, 0
	global_load_dwordx4 v[196:199], v184, s[100:101]
	global_load_dwordx4 v[200:203], v184, s[100:101] offset:256
	s_add_u32 s100, s100, 0x10000
	s_addc_u32 s101, s101, 0
	global_load_dwordx4 v[204:207], v184, s[100:101]
	global_load_dwordx4 v[218:221], v184, s[100:101] offset:256
	s_waitcnt vmcnt(0)
	s_mov_b32 s3, 0x90000
	v_lshl_add_u64 v[66:67], v[156:157], 0, s[18:19]
	s_mov_b64 s[18:19], 0x90000
	v_lshlrev_b32_e32 v74, 16, v176
	v_and_b32_e32 v75, 0xffff0000, v176
	v_lshlrev_b32_e32 v68, 16, v177
	v_and_b32_e32 v69, 0xffff0000, v177
	v_lshlrev_b32_e32 v76, 16, v178
	v_and_b32_e32 v77, 0xffff0000, v178
	v_lshlrev_b32_e32 v70, 16, v179
	v_and_b32_e32 v71, 0xffff0000, v179
	v_pk_mul_f32 v[68:69], v[68:69], s[60:61] op_sel_hi:[1,0]
	v_pk_mul_f32 v[74:75], v[74:75], s[60:61] op_sel_hi:[1,0]
	v_pk_fma_f32 v[64:65], v[64:65], v[152:153], v[68:69]
	v_pk_mul_f32 v[68:69], v[76:77], s[60:61] op_sel_hi:[1,0]
	v_pk_mul_f32 v[70:71], v[70:71], s[60:61] op_sel_hi:[1,0]
	v_pk_fma_f32 v[62:63], v[62:63], v[154:155], v[74:75]
	v_pk_fma_f32 v[70:71], v[60:61], v[148:149], v[70:71]
	v_pk_fma_f32 v[60:61], v[58:59], v[150:151], v[68:69]
	v_cvt_pk_bf16_f32 v58, v62, v63
	v_cvt_pk_bf16_f32 v59, v64, v65
	v_cvt_pk_bf16_f32 v60, v60, v61
	v_cvt_pk_bf16_f32 v61, v70, v71
	global_store_dwordx4 v[72:73], v[58:61], off
	v_lshlrev_b32_e32 v62, 16, v180
	v_and_b32_e32 v63, 0xffff0000, v180
	v_lshlrev_b32_e32 v58, 16, v181
	v_and_b32_e32 v59, 0xffff0000, v181
	v_lshlrev_b32_e32 v64, 16, v182
	v_and_b32_e32 v65, 0xffff0000, v182
	v_lshlrev_b32_e32 v60, 16, v183
	v_and_b32_e32 v61, 0xffff0000, v183
	v_pk_mul_f32 v[58:59], v[58:59], s[60:61] op_sel_hi:[1,0]
	v_pk_mul_f32 v[62:63], v[62:63], s[60:61] op_sel_hi:[1,0]
	v_pk_fma_f32 v[56:57], v[56:57], v[144:145], v[58:59]
	v_pk_mul_f32 v[58:59], v[64:65], s[60:61] op_sel_hi:[1,0]
	v_pk_mul_f32 v[60:61], v[60:61], s[60:61] op_sel_hi:[1,0]
	v_pk_fma_f32 v[54:55], v[54:55], v[146:147], v[62:63]
	v_pk_fma_f32 v[60:61], v[52:53], v[140:141], v[60:61]
	v_pk_fma_f32 v[52:53], v[50:51], v[142:143], v[58:59]
	v_cvt_pk_bf16_f32 v51, v56, v57
	v_add_co_u32_e32 v56, vcc, s3, v156
	v_cvt_pk_bf16_f32 v50, v54, v55
	v_cvt_pk_bf16_f32 v52, v52, v53
	v_cvt_pk_bf16_f32 v53, v60, v61
	v_addc_co_u32_e32 v57, vcc, 0, v157, vcc
	global_store_dwordx4 v[66:67], v[50:53], off offset:256
	s_nop 0
	s_mov_b32 s3, 0xa0000
	v_lshl_add_u64 v[50:51], v[156:157], 0, s[18:19]
	s_mov_b64 s[18:19], 0xa0000
	v_lshlrev_b32_e32 v58, 16, v188
	v_and_b32_e32 v59, 0xffff0000, v188
	v_lshlrev_b32_e32 v52, 16, v189
	v_and_b32_e32 v53, 0xffff0000, v189
	v_lshlrev_b32_e32 v60, 16, v190
	v_and_b32_e32 v61, 0xffff0000, v190
	v_lshlrev_b32_e32 v54, 16, v191
	v_and_b32_e32 v55, 0xffff0000, v191
	v_pk_mul_f32 v[52:53], v[52:53], s[60:61] op_sel_hi:[1,0]
	v_pk_mul_f32 v[58:59], v[58:59], s[60:61] op_sel_hi:[1,0]
	v_pk_fma_f32 v[48:49], v[48:49], v[152:153], v[52:53]
	v_pk_mul_f32 v[52:53], v[60:61], s[60:61] op_sel_hi:[1,0]
	v_pk_mul_f32 v[54:55], v[54:55], s[60:61] op_sel_hi:[1,0]
	v_pk_fma_f32 v[46:47], v[46:47], v[154:155], v[58:59]
	v_pk_fma_f32 v[54:55], v[44:45], v[148:149], v[54:55]
	v_pk_fma_f32 v[44:45], v[42:43], v[150:151], v[52:53]
	v_cvt_pk_bf16_f32 v42, v46, v47
	v_cvt_pk_bf16_f32 v43, v48, v49
	v_cvt_pk_bf16_f32 v44, v44, v45
	v_cvt_pk_bf16_f32 v45, v54, v55
	global_store_dwordx4 v[56:57], v[42:45], off
	v_lshlrev_b32_e32 v46, 16, v192
	v_and_b32_e32 v47, 0xffff0000, v192
	v_lshlrev_b32_e32 v42, 16, v193
	v_and_b32_e32 v43, 0xffff0000, v193
	v_lshlrev_b32_e32 v48, 16, v194
	v_and_b32_e32 v49, 0xffff0000, v194
	v_lshlrev_b32_e32 v44, 16, v195
	v_and_b32_e32 v45, 0xffff0000, v195
	v_pk_mul_f32 v[42:43], v[42:43], s[60:61] op_sel_hi:[1,0]
	v_pk_mul_f32 v[46:47], v[46:47], s[60:61] op_sel_hi:[1,0]
	v_pk_fma_f32 v[40:41], v[40:41], v[144:145], v[42:43]
	v_pk_mul_f32 v[42:43], v[48:49], s[60:61] op_sel_hi:[1,0]
	v_pk_mul_f32 v[44:45], v[44:45], s[60:61] op_sel_hi:[1,0]
	v_pk_fma_f32 v[38:39], v[38:39], v[146:147], v[46:47]
	v_pk_fma_f32 v[44:45], v[36:37], v[140:141], v[44:45]
	v_pk_fma_f32 v[36:37], v[34:35], v[142:143], v[42:43]
	v_cvt_pk_bf16_f32 v35, v40, v41
	v_add_co_u32_e32 v40, vcc, s3, v156
	v_cvt_pk_bf16_f32 v34, v38, v39
	v_cvt_pk_bf16_f32 v36, v36, v37
	v_cvt_pk_bf16_f32 v37, v44, v45
	v_addc_co_u32_e32 v41, vcc, 0, v157, vcc
	global_store_dwordx4 v[50:51], v[34:37], off offset:256
	s_nop 0
	s_mov_b32 s3, 0xb0000
	v_lshl_add_u64 v[34:35], v[156:157], 0, s[18:19]
	s_mov_b64 s[18:19], 0xb0000
	v_lshlrev_b32_e32 v42, 16, v196
	v_and_b32_e32 v43, 0xffff0000, v196
	v_lshlrev_b32_e32 v36, 16, v197
	v_and_b32_e32 v37, 0xffff0000, v197
	v_lshlrev_b32_e32 v44, 16, v198
	v_and_b32_e32 v45, 0xffff0000, v198
	v_lshlrev_b32_e32 v38, 16, v199
	v_and_b32_e32 v39, 0xffff0000, v199
	v_pk_mul_f32 v[36:37], v[36:37], s[60:61] op_sel_hi:[1,0]
	v_pk_mul_f32 v[42:43], v[42:43], s[60:61] op_sel_hi:[1,0]
	v_pk_fma_f32 v[32:33], v[32:33], v[152:153], v[36:37]
	v_pk_mul_f32 v[36:37], v[44:45], s[60:61] op_sel_hi:[1,0]
	v_pk_mul_f32 v[38:39], v[38:39], s[60:61] op_sel_hi:[1,0]
	v_pk_fma_f32 v[30:31], v[30:31], v[154:155], v[42:43]
	v_pk_fma_f32 v[38:39], v[28:29], v[148:149], v[38:39]
	v_pk_fma_f32 v[28:29], v[26:27], v[150:151], v[36:37]
	v_cvt_pk_bf16_f32 v26, v30, v31
	v_cvt_pk_bf16_f32 v27, v32, v33
	v_cvt_pk_bf16_f32 v28, v28, v29
	v_cvt_pk_bf16_f32 v29, v38, v39
	global_store_dwordx4 v[40:41], v[26:29], off
	v_lshlrev_b32_e32 v30, 16, v200
	v_and_b32_e32 v31, 0xffff0000, v200
	v_lshlrev_b32_e32 v26, 16, v201
	v_and_b32_e32 v27, 0xffff0000, v201
	v_lshlrev_b32_e32 v32, 16, v202
	v_and_b32_e32 v33, 0xffff0000, v202
	v_lshlrev_b32_e32 v28, 16, v203
	v_and_b32_e32 v29, 0xffff0000, v203
	v_pk_mul_f32 v[26:27], v[26:27], s[60:61] op_sel_hi:[1,0]
	v_pk_mul_f32 v[30:31], v[30:31], s[60:61] op_sel_hi:[1,0]
	v_pk_fma_f32 v[24:25], v[24:25], v[144:145], v[26:27]
	v_pk_mul_f32 v[26:27], v[32:33], s[60:61] op_sel_hi:[1,0]
	v_pk_mul_f32 v[28:29], v[28:29], s[60:61] op_sel_hi:[1,0]
	v_pk_fma_f32 v[22:23], v[22:23], v[146:147], v[30:31]
	v_pk_fma_f32 v[28:29], v[20:21], v[140:141], v[28:29]
	v_pk_fma_f32 v[20:21], v[18:19], v[142:143], v[26:27]
	v_cvt_pk_bf16_f32 v19, v24, v25
	v_add_co_u32_e32 v24, vcc, s3, v156
	v_cvt_pk_bf16_f32 v18, v22, v23
	v_cvt_pk_bf16_f32 v20, v20, v21
	v_cvt_pk_bf16_f32 v21, v28, v29
	v_addc_co_u32_e32 v25, vcc, 0, v157, vcc
	global_store_dwordx4 v[34:35], v[18:21], off offset:256
	s_nop 0
	s_andn2_b64 vcc, exec, s[0:1]
	v_lshl_add_u64 v[18:19], v[156:157], 0, s[18:19]
	s_mov_b64 s[18:19], -1
	v_lshlrev_b32_e32 v26, 16, v204
	v_and_b32_e32 v27, 0xffff0000, v204
	v_lshlrev_b32_e32 v20, 16, v205
	v_and_b32_e32 v21, 0xffff0000, v205
	v_lshlrev_b32_e32 v28, 16, v206
	v_and_b32_e32 v29, 0xffff0000, v206
	v_lshlrev_b32_e32 v22, 16, v207
	v_and_b32_e32 v23, 0xffff0000, v207
	v_pk_mul_f32 v[20:21], v[20:21], s[60:61] op_sel_hi:[1,0]
	v_pk_mul_f32 v[26:27], v[26:27], s[60:61] op_sel_hi:[1,0]
	v_pk_fma_f32 v[16:17], v[16:17], v[152:153], v[20:21]
	v_pk_mul_f32 v[20:21], v[28:29], s[60:61] op_sel_hi:[1,0]
	v_pk_mul_f32 v[22:23], v[22:23], s[60:61] op_sel_hi:[1,0]
	v_pk_fma_f32 v[14:15], v[14:15], v[154:155], v[26:27]
	v_pk_fma_f32 v[22:23], v[12:13], v[148:149], v[22:23]
	v_pk_fma_f32 v[12:13], v[10:11], v[150:151], v[20:21]
	v_cvt_pk_bf16_f32 v10, v14, v15
	v_cvt_pk_bf16_f32 v11, v16, v17
	v_cvt_pk_bf16_f32 v12, v12, v13
	v_cvt_pk_bf16_f32 v13, v22, v23
	global_store_dwordx4 v[24:25], v[10:13], off
	v_lshlrev_b32_e32 v14, 16, v218
	v_and_b32_e32 v15, 0xffff0000, v218
	v_lshlrev_b32_e32 v10, 16, v219
	v_and_b32_e32 v11, 0xffff0000, v219
	v_lshlrev_b32_e32 v16, 16, v220
	v_and_b32_e32 v17, 0xffff0000, v220
	v_lshlrev_b32_e32 v12, 16, v221
	v_and_b32_e32 v13, 0xffff0000, v221
	v_pk_mul_f32 v[10:11], v[10:11], s[60:61] op_sel_hi:[1,0]
	v_pk_mul_f32 v[14:15], v[14:15], s[60:61] op_sel_hi:[1,0]
	v_pk_fma_f32 v[8:9], v[8:9], v[144:145], v[10:11]
	v_pk_mul_f32 v[10:11], v[16:17], s[60:61] op_sel_hi:[1,0]
	v_pk_mul_f32 v[12:13], v[12:13], s[60:61] op_sel_hi:[1,0]
	v_pk_fma_f32 v[6:7], v[6:7], v[146:147], v[14:15]
	v_pk_fma_f32 v[12:13], v[4:5], v[140:141], v[12:13]
	v_pk_fma_f32 v[4:5], v[2:3], v[142:143], v[10:11]
	v_cvt_pk_bf16_f32 v2, v6, v7
	v_cvt_pk_bf16_f32 v3, v8, v9
	v_cvt_pk_bf16_f32 v4, v4, v5
	v_cvt_pk_bf16_f32 v5, v12, v13
	global_store_dwordx4 v[18:19], v[2:5], off offset:256
	s_cbranch_vccnz .LBB0_1038
	s_andn2_b64 vcc, exec, s[4:5]
	s_cbranch_vccnz .LBB0_1037
	s_barrier
	s_branch .LBB0_1037

	.amdhsa_kernel _Z10fwd_kernel6Params
		.amdhsa_group_segment_fixed_size 0
		.amdhsa_private_segment_fixed_size 0
		.amdhsa_kernarg_size 488
		.amdhsa_user_sgpr_count 2
		.amdhsa_user_sgpr_dispatch_ptr 0
		.amdhsa_user_sgpr_queue_ptr 0
		.amdhsa_user_sgpr_kernarg_segment_ptr 1
		.amdhsa_user_sgpr_dispatch_id 0
		.amdhsa_user_sgpr_kernarg_preload_length 0
		.amdhsa_user_sgpr_kernarg_preload_offset 0
		.amdhsa_user_sgpr_private_segment_size 0
		.amdhsa_uses_dynamic_stack 0
		.amdhsa_enable_private_segment 0
		.amdhsa_system_sgpr_workgroup_id_x 1
		.amdhsa_system_sgpr_workgroup_id_y 0
		.amdhsa_system_sgpr_workgroup_id_z 0
		.amdhsa_system_sgpr_workgroup_info 0
		.amdhsa_system_vgpr_workitem_id 2
		.amdhsa_next_free_vgpr 256
		.amdhsa_next_free_sgpr 102
		.amdhsa_accum_offset 256
		.amdhsa_reserve_vcc 1
		.amdhsa_float_round_mode_32 0
		.amdhsa_float_round_mode_16_64 0
		.amdhsa_float_denorm_mode_32 3
		.amdhsa_float_denorm_mode_16_64 3
		.amdhsa_dx10_clamp 1
		.amdhsa_ieee_mode 1
		.amdhsa_fp16_overflow 0
		.amdhsa_tg_split 0
		.amdhsa_exception_fp_ieee_invalid_op 0
		.amdhsa_exception_fp_denorm_src 0
		.amdhsa_exception_fp_ieee_div_zero 0
		.amdhsa_exception_fp_ieee_overflow 0
		.amdhsa_exception_fp_ieee_underflow 0
		.amdhsa_exception_fp_ieee_inexact 0
		.amdhsa_exception_int_div_zero 0
	.end_amdhsa_kernel

amdhsa.kernels:
  - .agpr_count:     0
    .args:
      - .offset:         0
        .size:           232
        .value_kind:     by_value
      - .offset:         232
        .size:           4
        .value_kind:     hidden_block_count_x
      - .offset:         236
        .size:           4
        .value_kind:     hidden_block_count_y
      - .offset:         240
        .size:           4
        .value_kind:     hidden_block_count_z
      - .offset:         244
        .size:           2
        .value_kind:     hidden_group_size_x
      - .offset:         246
        .size:           2
        .value_kind:     hidden_group_size_y
      - .offset:         248
        .size:           2
        .value_kind:     hidden_group_size_z
      - .offset:         250
        .size:           2
        .value_kind:     hidden_remainder_x
      - .offset:         252
        .size:           2
        .value_kind:     hidden_remainder_y
      - .offset:         254
        .size:           2
        .value_kind:     hidden_remainder_z
      - .offset:         272
        .size:           8
        .value_kind:     hidden_global_offset_x
      - .offset:         280
        .size:           8
        .value_kind:     hidden_global_offset_y
      - .offset:         288
        .size:           8
        .value_kind:     hidden_global_offset_z
      - .offset:         296
        .size:           2
        .value_kind:     hidden_grid_dims
      - .offset:         320
        .size:           8
        .value_kind:     hidden_multigrid_sync_arg
      - .offset:         352
        .size:           4
        .value_kind:     hidden_dynamic_lds_size
    .group_segment_fixed_size: 0
    .kernarg_segment_align: 8
    .kernarg_segment_size: 488
    .language:       OpenCL C
    .language_version:
      - 2
      - 0
    .max_flat_workgroup_size: 512
    .name:           _Z10fwd_kernel6Params
    .private_segment_fixed_size: 0
    .sgpr_count:     108
    .sgpr_spill_count: 163
    .symbol:         _Z10fwd_kernel6Params.kd
    .uniform_work_group_size: 1
    .uses_dynamic_stack: false
    .vgpr_count:     256
    .vgpr_spill_count: 0
    .wavefront_size: 64
